# up-phase weight conversion paced (s_sleep 32 per item) to reduce interference with the last GEMM round; on top of flat barrier release + LDS-image layouts
# baseline (speedup 1.0000x reference)
.LBB0_1776:
	s_sleep 32
	s_add_i32 s13, s12, s10
	s_cmpk_gt_i32 s13, 0x5aff
	s_cbranch_scc1 .LBB0_1775
	s_cmpk_gt_i32 s13, 0x12ff
	s_mov_b64 s[10:11], -1
	s_cbranch_scc0 .LBB0_1787
	s_cmpk_gt_u32 s13, 0x1aff
	s_cbranch_scc0 .LBB0_1784
	s_cmpk_gt_u32 s13, 0x3aff
	s_cbranch_scc0 .LBB0_1781
	s_and_b32 s10, s13, 0x7fffffc0
	s_addk_i32 s10, 0xc500
	s_lshl_b32 s11, s13, 5
	s_and_b32 s14, s11, 0x7e0
	v_add_u32_e32 v24, s10, v1
	s_lshl_b32 s90, s14, 2
	v_ashrrev_i32_e32 v25, 31, v24
	v_lshl_add_u64 v[32:33], v[6:7], 0, s[90:91]
	v_lshlrev_b64 v[24:25], 13, v[24:25]
	v_lshl_add_u64 v[24:25], v[32:33], 0, v[24:25]
	v_add_co_u32_e32 v32, vcc, 0x4000, v24
	global_load_dword v5, v[24:25], off nt
	s_nop 0
	v_addc_co_u32_e32 v33, vcc, 0, v25, vcc
	global_load_dword v11, v[32:33], off nt
	v_add_co_u32_e32 v32, vcc, 0x8000, v24
	s_mov_b32 s11, 0xc000
	s_nop 0
	v_addc_co_u32_e32 v33, vcc, 0, v25, vcc
	global_load_dword v18, v[32:33], off nt
	v_add_co_u32_e32 v32, vcc, s11, v24
	s_mov_b32 s11, 0x10000
	s_nop 0
	v_addc_co_u32_e32 v33, vcc, 0, v25, vcc
	global_load_dword v31, v[32:33], off nt
	v_add_co_u32_e32 v32, vcc, s11, v24
	s_mov_b32 s11, 0x14000
	s_nop 0
	v_addc_co_u32_e32 v33, vcc, 0, v25, vcc
	global_load_dword v34, v[32:33], off nt
	v_add_co_u32_e32 v32, vcc, s11, v24
	s_mov_b32 s11, 0x18000
	s_nop 0
	v_addc_co_u32_e32 v33, vcc, 0, v25, vcc
	global_load_dword v35, v[32:33], off nt
	v_add_co_u32_e32 v32, vcc, s11, v24
	s_mov_b32 s11, 0x1c000
	s_nop 0
	v_addc_co_u32_e32 v33, vcc, 0, v25, vcc
	global_load_dword v36, v[32:33], off nt
	v_add_co_u32_e32 v32, vcc, s11, v24
	s_mov_b32 s11, 0x20000
	s_nop 0
	v_addc_co_u32_e32 v33, vcc, 0, v25, vcc
	global_load_dword v37, v[32:33], off nt
	v_add_co_u32_e32 v32, vcc, s11, v24
	s_mov_b32 s11, 0x58000
	s_nop 0
	v_addc_co_u32_e32 v33, vcc, 0, v25, vcc
	global_load_dword v38, v[32:33], off nt
	v_add_co_u32_e32 v32, vcc, s19, v24
	s_lshr_b32 s90, s10, 6
	s_nop 0
	v_addc_co_u32_e32 v33, vcc, 0, v25, vcc
	global_load_dword v39, v[32:33], off nt
	v_add_co_u32_e32 v32, vcc, s20, v24
	s_nop 1
	v_addc_co_u32_e32 v33, vcc, 0, v25, vcc
	global_load_dword v40, v[32:33], off nt
	v_add_co_u32_e32 v32, vcc, s21, v24
	s_nop 1
	v_addc_co_u32_e32 v33, vcc, 0, v25, vcc
	global_load_dword v41, v[32:33], off nt
	v_add_co_u32_e32 v32, vcc, s22, v24
	s_nop 1
	v_addc_co_u32_e32 v33, vcc, 0, v25, vcc
	global_load_dword v42, v[32:33], off nt
	v_add_co_u32_e32 v32, vcc, s23, v24
	s_nop 1
	v_addc_co_u32_e32 v33, vcc, 0, v25, vcc
	global_load_dword v43, v[32:33], off nt
	v_add_co_u32_e32 v32, vcc, s24, v24
	s_nop 1
	v_addc_co_u32_e32 v33, vcc, 0, v25, vcc
	global_load_dword v44, v[32:33], off nt
	v_add_co_u32_e32 v32, vcc, s25, v24
	s_nop 1
	v_addc_co_u32_e32 v33, vcc, 0, v25, vcc
	global_load_dword v45, v[32:33], off nt
	v_add_co_u32_e32 v32, vcc, s26, v24
	s_nop 1
	v_addc_co_u32_e32 v33, vcc, 0, v25, vcc
	global_load_dword v46, v[32:33], off nt
	v_add_co_u32_e32 v32, vcc, s27, v24
	s_nop 1
	v_addc_co_u32_e32 v33, vcc, 0, v25, vcc
	global_load_dword v47, v[32:33], off nt
	v_add_co_u32_e32 v32, vcc, s43, v24
	s_nop 1
	v_addc_co_u32_e32 v33, vcc, 0, v25, vcc
	global_load_dword v48, v[32:33], off nt
	v_add_co_u32_e32 v32, vcc, s44, v24
	s_nop 1
	v_addc_co_u32_e32 v33, vcc, 0, v25, vcc
	global_load_dword v49, v[32:33], off nt
	v_add_co_u32_e32 v32, vcc, s45, v24
	s_nop 1
	v_addc_co_u32_e32 v33, vcc, 0, v25, vcc
	global_load_dword v50, v[32:33], off nt
	v_add_co_u32_e32 v32, vcc, s46, v24
	s_nop 1
	v_addc_co_u32_e32 v33, vcc, 0, v25, vcc
	global_load_dword v51, v[32:33], off nt
	v_add_co_u32_e32 v32, vcc, s11, v24
	s_mov_b32 s11, 0x5c000
	s_nop 0
	v_addc_co_u32_e32 v33, vcc, 0, v25, vcc
	global_load_dword v52, v[32:33], off nt
	v_add_co_u32_e32 v32, vcc, s11, v24
	s_mov_b32 s11, 0x60000
	s_nop 0
	v_addc_co_u32_e32 v33, vcc, 0, v25, vcc
	global_load_dword v53, v[32:33], off nt
	v_add_co_u32_e32 v32, vcc, s11, v24
	s_mov_b32 s11, 0x64000
	s_nop 0
	v_addc_co_u32_e32 v33, vcc, 0, v25, vcc
	global_load_dword v54, v[32:33], off nt
	v_add_co_u32_e32 v32, vcc, s11, v24
	s_mov_b32 s11, 0x68000
	s_nop 0
	v_addc_co_u32_e32 v33, vcc, 0, v25, vcc
	global_load_dword v55, v[32:33], off nt
	v_add_co_u32_e32 v32, vcc, s11, v24
	s_mov_b32 s11, 0x6c000
	s_nop 0
	v_addc_co_u32_e32 v33, vcc, 0, v25, vcc
	global_load_dword v56, v[32:33], off nt
	v_add_co_u32_e32 v32, vcc, s11, v24
	s_mov_b32 s11, 0x70000
	s_nop 0
	v_addc_co_u32_e32 v33, vcc, 0, v25, vcc
	global_load_dword v57, v[32:33], off nt
	v_add_co_u32_e32 v32, vcc, s11, v24
	s_mov_b32 s11, 0x74000
	s_nop 0
	v_addc_co_u32_e32 v33, vcc, 0, v25, vcc
	global_load_dword v58, v[32:33], off nt
	v_add_co_u32_e32 v32, vcc, s11, v24
	s_mov_b32 s11, 0x78000
	s_nop 0
	v_addc_co_u32_e32 v33, vcc, 0, v25, vcc
	global_load_dword v59, v[32:33], off nt
	v_add_co_u32_e32 v32, vcc, s11, v24
	s_mov_b32 s11, 0x7c000
	s_nop 0
	v_addc_co_u32_e32 v33, vcc, 0, v25, vcc
	v_add_co_u32_e32 v24, vcc, s11, v24
	global_load_dword v32, v[32:33], off nt
	s_nop 0
	v_addc_co_u32_e32 v25, vcc, 0, v25, vcc
	global_load_dword v24, v[24:25], off nt
	s_waitcnt vmcnt(0)
	ds_write2_b32 v3, v5, v11 offset1:66
	ds_write2_b32 v3, v18, v31 offset0:132 offset1:198
	v_add_u32_e32 v5, 0x400, v3
	ds_write2_b32 v5, v34, v35 offset0:8 offset1:74
	ds_write2_b32 v5, v36, v37 offset0:140 offset1:206
	v_add_u32_e32 v5, 0x800, v3
	ds_write2_b32 v5, v38, v39 offset0:16 offset1:82
	ds_write2_b32 v5, v40, v41 offset0:148 offset1:214
	v_add_u32_e32 v5, 0xc00, v3
	ds_write2_b32 v5, v42, v43 offset0:24 offset1:90
	ds_write2_b32 v5, v44, v45 offset0:156 offset1:222
	v_add_u32_e32 v5, 0x1000, v3
	ds_write2_b32 v5, v46, v47 offset0:32 offset1:98
	ds_write2_b32 v5, v48, v49 offset0:164 offset1:230
	v_add_u32_e32 v5, 0x1400, v3
	ds_write2_b32 v5, v50, v51 offset0:40 offset1:106
	ds_write2_b32 v5, v52, v53 offset0:172 offset1:238
	v_add_u32_e32 v5, 0x1800, v3
	ds_write2_b32 v5, v54, v55 offset0:48 offset1:114
	ds_write2_b32 v5, v56, v57 offset0:180 offset1:246
	v_add_u32_e32 v5, 0x1c00, v3
	ds_write2_b32 v5, v58, v59 offset0:56 offset1:122
	ds_write2_b32 v5, v32, v24 offset0:188 offset1:254
	s_waitcnt lgkmcnt(0)
	v_and_b32_e32 v70, 3, v146
	v_mul_u32_u24_e32 v70, 0x420, v70
	v_lshrrev_b32_e32 v71, 4, v146
	v_lshl_add_u32 v70, v71, 5, v70
	v_bfe_u32 v71, v146, 2, 2
	v_lshl_add_u32 v70, v71, 2, v70
	s_lshl_b32 s100, s42, 14
	v_add_u32_e32 v70, s100, v70
	v_add_u32_e32 v71, 0x1080, v70
	ds_read2_b32 v[24:25], v70 offset0:33 offset1:37
	ds_read2_b32 v[36:37], v70 offset1:4
	ds_read2_b32 v[38:39], v70 offset0:66 offset1:70
	ds_read2_b32 v[40:41], v70 offset0:99 offset1:103
	ds_read2_b32 v[42:43], v70 offset0:132 offset1:136
	ds_read2_b32 v[44:45], v70 offset0:165 offset1:169
	ds_read2_b32 v[46:47], v70 offset0:198 offset1:202
	ds_read2_b32 v[48:49], v70 offset0:231 offset1:235
	s_waitcnt lgkmcnt(7)
	v_bfe_u32 v11, v24, 16, 1
	s_waitcnt lgkmcnt(6)
	v_bfe_u32 v5, v36, 16, 1
	v_add3_u32 v5, v36, v5, s79
	v_lshrrev_b32_e32 v5, 16, v5
	v_add3_u32 v11, v24, v11, s79
	v_and_or_b32 v32, v11, s80, v5
	s_waitcnt lgkmcnt(5)
	v_bfe_u32 v5, v38, 16, 1
	v_add3_u32 v5, v38, v5, s79
	s_waitcnt lgkmcnt(4)
	v_bfe_u32 v11, v40, 16, 1
	v_lshrrev_b32_e32 v5, 16, v5
	v_add3_u32 v11, v40, v11, s79
	v_and_or_b32 v33, v11, s80, v5
	s_waitcnt lgkmcnt(3)
	v_bfe_u32 v5, v42, 16, 1
	v_add3_u32 v5, v42, v5, s79
	s_waitcnt lgkmcnt(2)
	v_bfe_u32 v11, v44, 16, 1
	v_lshrrev_b32_e32 v5, 16, v5
	v_add3_u32 v11, v44, v11, s79
	v_and_or_b32 v34, v11, s80, v5
	s_waitcnt lgkmcnt(1)
	v_bfe_u32 v5, v46, 16, 1
	v_add3_u32 v5, v46, v5, s79
	s_waitcnt lgkmcnt(0)
	v_bfe_u32 v11, v48, 16, 1
	v_lshrrev_b32_e32 v5, 16, v5
	v_add3_u32 v11, v48, v11, s79
	v_and_or_b32 v35, v11, s80, v5
	v_add_u32_e32 v5, s14, v26
	v_ashrrev_i32_e32 v50, 8, v5
	v_ashrrev_i32_e32 v51, 31, v50
	v_lshlrev_b64 v[50:51], 22, v[50:51]
	s_lshl_b64 s[10:11], s[90:91], 15
	s_lshr_b32 s100, s14, 8
	s_lshl_b32 s100, s100, 22
	s_bfe_u32 s101, s14, 0x10007
	s_lshl_b32 s101, s101, 14
	s_add_i32 s100, s100, s101
	s_bfe_u32 s101, s14, 0x20005
	s_lshl_b32 s101, s101, 12
	s_add_i32 s100, s100, s101
	v_lshrrev_b32_e32 v62, 5, v146
	v_lshlrev_b32_e32 v62, 5, v62
	v_lshlrev_b32_e32 v64, 4, v146
	v_xor_b32_e32 v62, v62, v64
	v_add_u32_e32 v62, s100, v62
	v_mov_b32_e32 v63, v19
	v_lshl_add_u64 v[68:69], s[0:1], 0, v[62:63]
	v_lshl_add_u64 v[68:69], v[68:69], 0, s[10:11]
	v_lshl_add_u64 v[50:51], s[0:1], 0, v[50:51]
	v_lshlrev_b32_e32 v5, 7, v5
	v_lshl_add_u64 v[50:51], v[50:51], 0, s[10:11]
	v_and_b32_e32 v18, 0x7f80, v5
	v_bfe_u32 v5, v37, 16, 1
	v_lshl_add_u64 v[50:51], v[50:51], 0, v[18:19]
	v_mov_b32_e32 v11, v19
	v_add3_u32 v5, v37, v5, s79
	v_bfe_u32 v18, v25, 16, 1
	v_lshl_add_u64 v[50:51], v[50:51], 0, v[10:11]
	v_lshrrev_b32_e32 v5, 16, v5
	v_add3_u32 v18, v25, v18, s79
	global_store_dwordx4 v[68:69], v[32:35], off nt
	s_nop 1
	v_and_or_b32 v32, v18, s80, v5
	v_bfe_u32 v5, v39, 16, 1
	v_add3_u32 v5, v39, v5, s79
	v_bfe_u32 v18, v41, 16, 1
	v_lshrrev_b32_e32 v5, 16, v5
	v_add3_u32 v18, v41, v18, s79
	v_and_or_b32 v33, v18, s80, v5
	v_bfe_u32 v5, v43, 16, 1
	v_add3_u32 v5, v43, v5, s79
	v_bfe_u32 v18, v45, 16, 1
	v_lshrrev_b32_e32 v5, 16, v5
	v_add3_u32 v18, v45, v18, s79
	v_and_or_b32 v34, v18, s80, v5
	v_bfe_u32 v5, v47, 16, 1
	v_add3_u32 v5, v47, v5, s79
	v_bfe_u32 v18, v49, 16, 1
	v_lshrrev_b32_e32 v5, 16, v5
	v_add3_u32 v18, v49, v18, s79
	v_and_or_b32 v35, v18, s80, v5
	v_add_u32_e32 v5, s14, v28
	v_ashrrev_i32_e32 v24, 8, v5
	v_ashrrev_i32_e32 v25, 31, v24
	v_lshlrev_b64 v[24:25], 22, v[24:25]
	v_lshl_add_u64 v[24:25], s[0:1], 0, v[24:25]
	v_lshlrev_b32_e32 v5, 7, v5
	v_lshl_add_u64 v[24:25], v[24:25], 0, s[10:11]
	v_and_b32_e32 v18, 0x7f80, v5
	v_lshl_add_u64 v[24:25], v[24:25], 0, v[18:19]
	v_lshl_add_u64 v[24:25], v[24:25], 0, v[10:11]
	global_store_dwordx4 v[68:69], v[32:35], off offset:2048 nt
	ds_read2_b32 v[24:25], v71 offset1:4
	ds_read2_b32 v[36:37], v71 offset0:33 offset1:37
	ds_read2_b32 v[38:39], v71 offset0:66 offset1:70
	ds_read2_b32 v[40:41], v71 offset0:99 offset1:103
	ds_read2_b32 v[42:43], v71 offset0:132 offset1:136
	ds_read2_b32 v[44:45], v71 offset0:165 offset1:169
	ds_read2_b32 v[46:47], v71 offset0:198 offset1:202
	ds_read2_b32 v[48:49], v71 offset0:231 offset1:235
	s_waitcnt lgkmcnt(7)
	v_bfe_u32 v5, v24, 16, 1
	v_add3_u32 v5, v24, v5, s79
	s_waitcnt lgkmcnt(6)
	v_bfe_u32 v18, v36, 16, 1
	v_lshrrev_b32_e32 v5, 16, v5
	v_add3_u32 v18, v36, v18, s79
	v_and_or_b32 v32, v18, s80, v5
	s_waitcnt lgkmcnt(5)
	v_bfe_u32 v5, v38, 16, 1
	v_add3_u32 v5, v38, v5, s79
	s_waitcnt lgkmcnt(4)
	v_bfe_u32 v18, v40, 16, 1
	v_lshrrev_b32_e32 v5, 16, v5
	v_add3_u32 v18, v40, v18, s79
	v_and_or_b32 v33, v18, s80, v5
	s_waitcnt lgkmcnt(3)
	v_bfe_u32 v5, v42, 16, 1
	v_add3_u32 v5, v42, v5, s79
	s_waitcnt lgkmcnt(2)
	v_bfe_u32 v18, v44, 16, 1
	v_lshrrev_b32_e32 v5, 16, v5
	v_add3_u32 v18, v44, v18, s79
	v_and_or_b32 v34, v18, s80, v5
	s_waitcnt lgkmcnt(1)
	v_bfe_u32 v5, v46, 16, 1
	v_add3_u32 v5, v46, v5, s79
	s_waitcnt lgkmcnt(0)
	v_bfe_u32 v18, v48, 16, 1
	v_lshrrev_b32_e32 v5, 16, v5
	v_add3_u32 v18, v48, v18, s79
	v_and_or_b32 v35, v18, s80, v5
	v_add_u32_e32 v5, s14, v29
	v_ashrrev_i32_e32 v50, 8, v5
	v_ashrrev_i32_e32 v51, 31, v50
	v_lshlrev_b64 v[50:51], 22, v[50:51]
	v_lshl_add_u64 v[50:51], s[0:1], 0, v[50:51]
	v_lshlrev_b32_e32 v5, 7, v5
	v_lshl_add_u64 v[50:51], v[50:51], 0, s[10:11]
	v_and_b32_e32 v18, 0x7f80, v5
	v_bfe_u32 v5, v25, 16, 1
	v_lshl_add_u64 v[50:51], v[50:51], 0, v[18:19]
	v_add3_u32 v5, v25, v5, s79
	v_bfe_u32 v18, v37, 16, 1
	v_lshl_add_u64 v[50:51], v[50:51], 0, v[10:11]
	v_lshrrev_b32_e32 v5, 16, v5
	v_add3_u32 v18, v37, v18, s79
	global_store_dwordx4 v[68:69], v[32:35], off offset:1024 nt
	s_nop 1
	v_and_or_b32 v32, v18, s80, v5
	v_bfe_u32 v5, v39, 16, 1
	v_add3_u32 v5, v39, v5, s79
	v_bfe_u32 v18, v41, 16, 1
	v_lshrrev_b32_e32 v5, 16, v5
	v_add3_u32 v18, v41, v18, s79
	v_and_or_b32 v33, v18, s80, v5
	v_bfe_u32 v5, v43, 16, 1
	v_add3_u32 v5, v43, v5, s79
	v_bfe_u32 v18, v45, 16, 1
	v_lshrrev_b32_e32 v5, 16, v5
	v_add3_u32 v18, v45, v18, s79
	v_and_or_b32 v34, v18, s80, v5
	v_bfe_u32 v5, v47, 16, 1
	v_add3_u32 v5, v47, v5, s79
	v_bfe_u32 v18, v49, 16, 1
	v_lshrrev_b32_e32 v5, 16, v5
	v_add3_u32 v18, v49, v18, s79
	v_and_or_b32 v35, v18, s80, v5
	v_add_u32_e32 v5, s14, v30
	v_ashrrev_i32_e32 v24, 8, v5
	v_ashrrev_i32_e32 v25, 31, v24
	v_lshlrev_b64 v[24:25], 22, v[24:25]
	v_lshl_add_u64 v[24:25], s[0:1], 0, v[24:25]
	v_lshlrev_b32_e32 v5, 7, v5
	v_lshl_add_u64 v[24:25], v[24:25], 0, s[10:11]
	v_and_b32_e32 v18, 0x7f80, v5
	v_lshl_add_u64 v[24:25], v[24:25], 0, v[18:19]
	v_lshl_add_u64 v[24:25], v[24:25], 0, v[10:11]
	global_store_dwordx4 v[68:69], v[32:35], off offset:3072 nt
	s_waitcnt lgkmcnt(0)
	s_mov_b64 s[10:11], 0
